# RWKV scan chunk prefetch: per-lane address parts kept in registers, one scalar chunk offset (3 VALU instead of 30 per chunk)
# speedup vs baseline: 1.0063x; 1.0049x over previous
; #define SC_GLOAD(ci_) { rg0 = SC_G1(ci_, 0); rg1 = SC_G1(ci_, 1); rg2 = SC_G1(ci_, 2); }
; #define SC_LSTORE(st_) { SC_S1(st_, 0, rg0) SC_S1(st_, 1, rg1) SC_S1(st_, 2, rg2) }
; __device__ __forceinline__ void rwkv_scan_unit(const Params& p, int unit, char* smem) {
;     ...
;     __syncthreads();
;     SC_GLOAD(0)
;     SC_LSTORE(0)
;     __syncthreads();
;     for (int ci = 0; ci < NCH; ++ci) {
;         const int st = (ci & 1) * STG;
;         if (ci + 1 < NCH) { SC_GLOAD(ci + 1) }
.LBB0_380:
	global_load_dword v39, v[152:153], off
	v_add_u32_e32 v87, 16, v87
	v_add_u32_e32 v85, 16, v85
	v_add_u32_e32 v83, 16, v83
	v_add_u32_e32 v88, -16, v88
	v_add_u32_e32 v86, -16, v86
	v_add_u32_e32 v84, -16, v84
	v_add_u32_e32 v142, s55, v87
	v_cmp_lt_i32_e32 vcc, s2, v142
	s_nop 1
	v_cndmask_b32_e32 v143, v196, v197, vcc
	v_add_u32_e32 v143, v143, v88
	v_cndmask_b32_e64 v142, v143, v142, s[44:45]
	v_ashrrev_i32_e32 v143, 31, v142
	v_lshl_add_u64 v[142:143], v[142:143], 0, s[88:89]
	v_lshlrev_b64 v[142:143], 9, v[142:143]
	v_lshl_add_u64 v[140:141], v[152:153], 0, v[142:143]
	global_load_dwordx4 v[140:143], v[140:141], off
	v_add_u32_e32 v146, s55, v85
	v_cmp_lt_i32_e32 vcc, s2, v146
	s_nop 1
	v_cndmask_b32_e32 v147, v196, v197, vcc
	v_add_u32_e32 v147, v147, v86
	v_cndmask_b32_e64 v146, v147, v146, s[44:45]
	v_ashrrev_i32_e32 v147, 31, v146
	v_lshl_add_u64 v[146:147], v[146:147], 0, s[88:89]
	v_lshlrev_b64 v[146:147], 9, v[146:147]
	v_lshl_add_u64 v[144:145], v[154:155], 0, v[146:147]
	global_load_dwordx4 v[144:147], v[144:145], off
	v_add_u32_e32 v150, s55, v83
	v_cmp_lt_i32_e32 vcc, s2, v150
	s_nop 1
	v_cndmask_b32_e32 v151, v196, v197, vcc
	v_add_u32_e32 v151, v151, v84
	v_cndmask_b32_e64 v150, v151, v150, s[44:45]
	v_ashrrev_i32_e32 v151, 31, v150
	v_lshl_add_u64 v[150:151], v[150:151], 0, s[88:89]
	v_lshlrev_b64 v[150:151], 9, v[150:151]
	v_lshl_add_u64 v[148:149], v[156:157], 0, v[150:151]
	global_load_dwordx4 v[148:151], v[148:149], off
	global_load_dword v39, v[152:153], off
	v_add_u32_e32 v87, 16, v87
	v_add_u32_e32 v85, 16, v85
	v_add_u32_e32 v83, 16, v83
	v_add_u32_e32 v88, -16, v88
	v_add_u32_e32 v86, -16, v86
	v_add_u32_e32 v84, -16, v84
	v_add_u32_e32 v126, s55, v87
	v_cmp_lt_i32_e32 vcc, s2, v126
	s_nop 1
	v_cndmask_b32_e32 v127, v196, v197, vcc
	v_add_u32_e32 v127, v127, v88
	v_cndmask_b32_e64 v126, v127, v126, s[44:45]
	v_ashrrev_i32_e32 v127, 31, v126
	v_lshl_add_u64 v[126:127], v[126:127], 0, s[88:89]
	v_lshlrev_b64 v[126:127], 9, v[126:127]
	v_lshl_add_u64 v[124:125], v[152:153], 0, v[126:127]
	global_load_dwordx4 v[124:127], v[124:125], off
	v_add_u32_e32 v130, s55, v85
	v_cmp_lt_i32_e32 vcc, s2, v130
	s_nop 1
	v_cndmask_b32_e32 v131, v196, v197, vcc
	v_add_u32_e32 v131, v131, v86
	v_cndmask_b32_e64 v130, v131, v130, s[44:45]
	v_ashrrev_i32_e32 v131, 31, v130
	v_lshl_add_u64 v[130:131], v[130:131], 0, s[88:89]
	v_lshlrev_b64 v[130:131], 9, v[130:131]
	v_lshl_add_u64 v[128:129], v[154:155], 0, v[130:131]
	global_load_dwordx4 v[128:131], v[128:129], off
	v_add_u32_e32 v134, s55, v83
	v_cmp_lt_i32_e32 vcc, s2, v134
	s_nop 1
	v_cndmask_b32_e32 v135, v196, v197, vcc
	v_add_u32_e32 v135, v135, v84
	v_cndmask_b32_e64 v134, v135, v134, s[44:45]
	v_ashrrev_i32_e32 v135, 31, v134
	v_lshl_add_u64 v[134:135], v[134:135], 0, s[88:89]
	v_lshlrev_b64 v[134:135], 9, v[134:135]
	v_lshl_add_u64 v[132:133], v[156:157], 0, v[134:135]
	global_load_dwordx4 v[132:135], v[132:133], off
	global_load_dword v39, v[152:153], off
	v_add_u32_e32 v87, 16, v87
	v_add_u32_e32 v85, 16, v85
	v_add_u32_e32 v83, 16, v83
	v_add_u32_e32 v88, -16, v88
	v_add_u32_e32 v86, -16, v86
	v_add_u32_e32 v84, -16, v84
	v_add_u32_e32 v230, s55, v88
	v_cndmask_b32_e64 v230, v230, v87, s[44:45]
	v_ashrrev_i32_e32 v231, 31, v230
	v_lshl_add_u64 v[230:231], v[230:231], 0, s[88:89]
	v_lshlrev_b64 v[230:231], 9, v[230:231]
	v_lshl_add_u64 v[224:225], v[152:153], 0, v[230:231]
	v_add_u32_e32 v230, s55, v86
	v_cndmask_b32_e64 v230, v230, v85, s[44:45]
	v_ashrrev_i32_e32 v231, 31, v230
	v_lshl_add_u64 v[230:231], v[230:231], 0, s[88:89]
	v_lshlrev_b64 v[230:231], 9, v[230:231]
	v_lshl_add_u64 v[226:227], v[154:155], 0, v[230:231]
	v_add_u32_e32 v230, s55, v84
	v_cndmask_b32_e64 v230, v230, v83, s[44:45]
	v_ashrrev_i32_e32 v231, 31, v230
	v_lshl_add_u64 v[230:231], v[230:231], 0, s[88:89]
	v_lshlrev_b64 v[230:231], 9, v[230:231]
	v_lshl_add_u64 v[228:229], v[156:157], 0, v[230:231]

; #define SC_GLOAD(ci_) { rg0 = SC_G1(ci_, 0); rg1 = SC_G1(ci_, 1); rg2 = SC_G1(ci_, 2); }
; __device__ __forceinline__ void rwkv_scan_unit(const Params& p, int unit, char* smem) {
;     ...
;         if (ci + 1 < NCH) { SC_GLOAD(ci + 1) }
.Lsc_p0_load:
	s_cmpk_ge_u32 s55, 0xc0
	s_movk_i32 s98, 0xff
	s_movk_i32 s99, 0x11ff
	s_cselect_b32 s98, s99, s98
	s_sub_u32 s98, s98, s55
	s_cmp_lg_u64 s[44:45], 0
	s_cselect_b32 s98, s55, s98
	s_lshl_b32 s98, s98, 9
	s_mov_b32 s99, 0
	v_lshl_add_u64 v[160:161], v[224:225], 0, s[98:99]
	global_load_dwordx4 v[160:163], v[160:161], off
	v_lshl_add_u64 v[164:165], v[226:227], 0, s[98:99]
	global_load_dwordx4 v[164:167], v[164:165], off
	v_lshl_add_u64 v[168:169], v[228:229], 0, s[98:99]
	global_load_dwordx4 v[168:171], v[168:169], off

; #define SC_GLOAD(ci_) { rg0 = SC_G1(ci_, 0); rg1 = SC_G1(ci_, 1); rg2 = SC_G1(ci_, 2); }
; __device__ __forceinline__ void rwkv_scan_unit(const Params& p, int unit, char* smem) {
;     ...
;         if (ci + 1 < NCH) { SC_GLOAD(ci + 1) }
.Lsc_p1_load:
	s_cmpk_ge_u32 s55, 0xc0
	s_movk_i32 s98, 0xff
	s_movk_i32 s99, 0x11ff
	s_cselect_b32 s98, s99, s98
	s_sub_u32 s98, s98, s55
	s_cmp_lg_u64 s[44:45], 0
	s_cselect_b32 s98, s55, s98
	s_lshl_b32 s98, s98, 9
	s_mov_b32 s99, 0
	v_lshl_add_u64 v[0:1], v[224:225], 0, s[98:99]
	global_load_dwordx4 v[0:3], v[0:1], off
	v_lshl_add_u64 v[4:5], v[226:227], 0, s[98:99]
	global_load_dwordx4 v[4:7], v[4:5], off
	v_lshl_add_u64 v[8:9], v[228:229], 0, s[98:99]
	global_load_dwordx4 v[8:11], v[8:9], off

; #define SC_GLOAD(ci_) { rg0 = SC_G1(ci_, 0); rg1 = SC_G1(ci_, 1); rg2 = SC_G1(ci_, 2); }
; __device__ __forceinline__ void rwkv_scan_unit(const Params& p, int unit, char* smem) {
;     ...
;         if (ci + 1 < NCH) { SC_GLOAD(ci + 1) }
.Lsc_p2_load:
	s_cmpk_ge_u32 s55, 0xc0
	s_movk_i32 s98, 0xff
	s_movk_i32 s99, 0x11ff
	s_cselect_b32 s98, s99, s98
	s_sub_u32 s98, s98, s55
	s_cmp_lg_u64 s[44:45], 0
	s_cselect_b32 s98, s55, s98
	s_lshl_b32 s98, s98, 9
	s_mov_b32 s99, 0
	v_lshl_add_u64 v[140:141], v[224:225], 0, s[98:99]
	global_load_dwordx4 v[140:143], v[140:141], off
	v_lshl_add_u64 v[144:145], v[226:227], 0, s[98:99]
	global_load_dwordx4 v[144:147], v[144:145], off
	v_lshl_add_u64 v[148:149], v[228:229], 0, s[98:99]
	global_load_dwordx4 v[148:151], v[148:149], off

; #define SC_GLOAD(ci_) { rg0 = SC_G1(ci_, 0); rg1 = SC_G1(ci_, 1); rg2 = SC_G1(ci_, 2); }
; __device__ __forceinline__ void rwkv_scan_unit(const Params& p, int unit, char* smem) {
;     ...
;         if (ci + 1 < NCH) { SC_GLOAD(ci + 1) }
.Lsc_p3_load:
	s_cmpk_ge_u32 s55, 0xc0
	s_movk_i32 s98, 0xff
	s_movk_i32 s99, 0x11ff
	s_cselect_b32 s98, s99, s98
	s_sub_u32 s98, s98, s55
	s_cmp_lg_u64 s[44:45], 0
	s_cselect_b32 s98, s55, s98
	s_lshl_b32 s98, s98, 9
	s_mov_b32 s99, 0
	v_lshl_add_u64 v[124:125], v[224:225], 0, s[98:99]
	global_load_dwordx4 v[124:127], v[124:125], off
	v_lshl_add_u64 v[128:129], v[226:227], 0, s[98:99]
	global_load_dwordx4 v[128:131], v[128:129], off
	v_lshl_add_u64 v[132:133], v[228:229], 0, s[98:99]
	global_load_dwordx4 v[132:135], v[132:133], off
